# saddr-form LDS-DMA addressing in W1, W2 and RetIn K-loops (no VALU in load phases), setprio flips removed
# speedup vs baseline: 1.0036x; 1.0036x over previous
; #define PG8_STAGE(bufoff, gbase, voff) do { _Pragma("unroll") for (int _i = 0; _i < 2; ++_i) \
;         __builtin_amdgcn_global_load_lds((const unsigned*)((const char*)(gbase) + (voff)[_i]), (LAS unsigned*)(lds + (bufoff) + ldsw + _i * 8192), 16, 0, 0); } while (0)
; #define PG8_LDA(dst, b, h) do { _Pragma("unroll") for (int m = 0; m < 4; ++m) _Pragma("unroll") for (int k = 0; k < 2; ++k) dst[m][k] = *(const LAS bf16x8*)(lds + PG8_SA(b, h) + aoff + m * 2048 + k * 1024); } while (0)
; #define PG8_LDB(dst, b, h) do { _Pragma("unroll") for (int n = 0; n < 2; ++n) _Pragma("unroll") for (int k = 0; k < 2; ++k) dst[n][k] = *(const LAS bf16x8*)(lds + PG8_SB(b, h) + boff + n * 2048 + k * 1024); } while (0)
; #define PG8_MMA(ai, bj, At, Bt) do { __builtin_amdgcn_s_setprio(1); _Pragma("unroll") for (int m = 0; m < 4; ++m) _Pragma("unroll") for (int n = 0; n < 2; ++n) _Pragma("unroll") for (int k = 0; k < 2; ++k) \
;         acc[ai][bj][m][n] = __builtin_amdgcn_mfma_f32_16x16x32_bf16(Bt[n][k], At[m][k], acc[ai][bj][m][n], 0, 0, 0); __builtin_amdgcn_s_setprio(0); } while (0)
; #define PG8_WAIT_V(n) asm volatile("s_waitcnt vmcnt(" #n ")" ::: "memory")
; #define PG8_WAIT_L(n) asm volatile("s_waitcnt lgkmcnt(" #n ")" ::: "memory")
; #define PG8_BAR __builtin_amdgcn_s_barrier()
; #define PG8_SCHED __builtin_amdgcn_sched_barrier(0)
; template <class Epi>
; __device__ __forceinline__ void gemm_phase(LAS unsigned char* lds, const Gemm g, const Epi& E) {
;     ...
;         for (int t = 0; t < nt; t += 2) {
;             const bool last = (t == nt - 2);
;             const char* a1 = cA + (size_t)(t + 1) * kstep;
;             const char* a2 = last ? nA : cA + (size_t)(t + 2) * kstep; const char* b2 = last ? nB : cB + (size_t)(t + 2) * kstep;
;             const char* a3 = a2 + kstep; const char* b3 = b2 + kstep;
;             PG8_LDB(B0, 0, 0); PG8_LDB(B1, 0, 1); PG8_SCHED; PG8_LDA(At, 0, 0); PG8_STAGE(PG8_SA(1, 1), a1 + hstepA, voffA);
;             PG8_WAIT_V(8); PG8_WAIT_L(0); PG8_BAR; PG8_MMA(0, 0, At, B0); PG8_MMA(0, 1, At, B1); PG8_BAR; PG8_SCHED;
;     ...
; #pragma unroll
;         for (int a = 0; a < 2; ++a)
; #pragma unroll
;             for (int b = 0; b < 2; ++b)
; #pragma unroll
;                 for (int m = 0; m < 4; ++m)
; #pragma unroll
;                     for (int n = 0; n < 2; ++n) acc[a][b][m][n] = (f32x4){0.f, 0.f, 0.f, 0.f};
.LBB0_500:
	s_add_u32 s76, s22, 0x100
	v_mov_b32_e32 v0, 0
	s_addc_u32 s77, s23, 0
	s_mov_b32 s82, -2
	s_waitcnt lgkmcnt(0)
	v_mov_b32_e32 v1, v0
	v_mov_b32_e32 v2, v0
	v_mov_b32_e32 v3, v0
	v_mov_b32_e32 v4, v0
	v_mov_b32_e32 v5, v0
	v_mov_b32_e32 v6, v0
	v_mov_b32_e32 v7, v0
	v_mov_b32_e32 v16, v0
	v_mov_b32_e32 v17, v0
	v_mov_b32_e32 v18, v0
	v_mov_b32_e32 v19, v0
	v_mov_b32_e32 v20, v0
	v_mov_b32_e32 v21, v0
	v_mov_b32_e32 v22, v0
	v_mov_b32_e32 v23, v0
	v_mov_b32_e32 v32, v0
	v_mov_b32_e32 v33, v0
	v_mov_b32_e32 v34, v0
	v_mov_b32_e32 v35, v0
	v_mov_b32_e32 v36, v0
	v_mov_b32_e32 v37, v0
	v_mov_b32_e32 v38, v0
	v_mov_b32_e32 v39, v0
	v_mov_b32_e32 v48, v0
	v_mov_b32_e32 v49, v0
	v_mov_b32_e32 v50, v0
	v_mov_b32_e32 v51, v0
	v_mov_b32_e32 v52, v0
	v_mov_b32_e32 v53, v0
	v_mov_b32_e32 v54, v0
	v_mov_b32_e32 v55, v0
	v_mov_b32_e32 v8, v0
	v_mov_b32_e32 v9, v0
	v_mov_b32_e32 v10, v0
	v_mov_b32_e32 v11, v0
	v_mov_b32_e32 v12, v0
	v_mov_b32_e32 v13, v0
	v_mov_b32_e32 v14, v0
	v_mov_b32_e32 v15, v0
	v_mov_b32_e32 v24, v0
	v_mov_b32_e32 v25, v0
	v_mov_b32_e32 v26, v0
	v_mov_b32_e32 v27, v0
	v_mov_b32_e32 v28, v0
	v_mov_b32_e32 v29, v0
	v_mov_b32_e32 v30, v0
	v_mov_b32_e32 v31, v0
	v_mov_b32_e32 v40, v0
	v_mov_b32_e32 v41, v0
	v_mov_b32_e32 v42, v0
	v_mov_b32_e32 v43, v0
	v_mov_b32_e32 v44, v0
	v_mov_b32_e32 v45, v0
	v_mov_b32_e32 v46, v0
	v_mov_b32_e32 v47, v0
	v_mov_b32_e32 v56, v0
	v_mov_b32_e32 v57, v0
	v_mov_b32_e32 v58, v0
	v_mov_b32_e32 v59, v0
	v_mov_b32_e32 v60, v0
	v_mov_b32_e32 v61, v0
	v_mov_b32_e32 v62, v0
	v_mov_b32_e32 v63, v0
	v_mov_b32_e32 v64, v0
	v_mov_b32_e32 v65, v0
	v_mov_b32_e32 v66, v0
	v_mov_b32_e32 v67, v0
	v_mov_b32_e32 v68, v0
	v_mov_b32_e32 v69, v0
	v_mov_b32_e32 v70, v0
	v_mov_b32_e32 v71, v0
	v_mov_b32_e32 v80, v0
	v_mov_b32_e32 v81, v0
	v_mov_b32_e32 v82, v0
	v_mov_b32_e32 v83, v0
	v_mov_b32_e32 v84, v0
	v_mov_b32_e32 v85, v0
	v_mov_b32_e32 v86, v0
	v_mov_b32_e32 v87, v0
	v_mov_b32_e32 v96, v0
	v_mov_b32_e32 v97, v0
	v_mov_b32_e32 v98, v0
	v_mov_b32_e32 v99, v0
	v_mov_b32_e32 v100, v0
	v_mov_b32_e32 v101, v0
	v_mov_b32_e32 v102, v0
	v_mov_b32_e32 v103, v0
	v_mov_b32_e32 v112, v0
	v_mov_b32_e32 v113, v0
	v_mov_b32_e32 v114, v0
	v_mov_b32_e32 v115, v0
	v_mov_b32_e32 v116, v0
	v_mov_b32_e32 v117, v0
	v_mov_b32_e32 v118, v0
	v_mov_b32_e32 v119, v0
	v_mov_b32_e32 v72, v0
	v_mov_b32_e32 v73, v0
	v_mov_b32_e32 v74, v0
	v_mov_b32_e32 v75, v0
	v_mov_b32_e32 v76, v0
	v_mov_b32_e32 v77, v0
	v_mov_b32_e32 v78, v0
	v_mov_b32_e32 v79, v0
	v_mov_b32_e32 v88, v0
	v_mov_b32_e32 v89, v0
	v_mov_b32_e32 v90, v0
	v_mov_b32_e32 v91, v0
	v_mov_b32_e32 v92, v0
	v_mov_b32_e32 v93, v0
	v_mov_b32_e32 v94, v0
	v_mov_b32_e32 v95, v0
	v_mov_b32_e32 v104, v0
	v_mov_b32_e32 v105, v0
	v_mov_b32_e32 v106, v0
	v_mov_b32_e32 v107, v0
	v_mov_b32_e32 v108, v0
	v_mov_b32_e32 v109, v0
	v_mov_b32_e32 v110, v0
	v_mov_b32_e32 v111, v0
	v_mov_b32_e32 v120, v0
	v_mov_b32_e32 v121, v0
	v_mov_b32_e32 v122, v0
	v_mov_b32_e32 v123, v0
	v_mov_b32_e32 v124, v0
	v_mov_b32_e32 v125, v0
	v_mov_b32_e32 v126, v0
	v_mov_b32_e32 v127, v0
	v_add_u32_e32 v182, 0x10000, v167
.LBB0_501:
	s_add_u32 s22, s20, 0x100
	s_addc_u32 s23, s21, 0
	s_cmp_eq_u32 s82, 40
	s_cselect_b32 s45, s35, s23
	s_cselect_b32 s44, s34, s22
	s_cselect_b32 s39, s37, s77
	s_cselect_b32 s38, s36, s76
	ds_read_b128 v[128:131], v182
	ds_read_b128 v[132:135], v182 offset:1024
	ds_read_b128 v[148:151], v182 offset:2048
	ds_read_b128 v[152:155], v182 offset:3072
	ds_read_b128 v[156:159], v182 offset:16384
	ds_read_b128 v[160:163], v182 offset:17408
	ds_read_b128 v[170:173], v182 offset:18432
	ds_read_b128 v[174:177], v182 offset:19456
	s_add_i32 m0, s48, 0xc000
	ds_read_b128 v[178:181], v169
	ds_read_b128 v[202:205], v169 offset:1024
	ds_read_b128 v[206:209], v169 offset:2048
	ds_read_b128 v[210:213], v169 offset:3072
	ds_read_b128 v[214:217], v169 offset:4096
	ds_read_b128 v[218:221], v169 offset:5120
	ds_read_b128 v[222:225], v169 offset:6144
	ds_read_b128 v[244:247], v169 offset:7168
	global_load_lds_dwordx4 v144, s[20:21]
	s_add_i32 m0, s48, 0xe000
	s_nop 0
	global_load_lds_dwordx4 v146, s[20:21]
	s_waitcnt vmcnt(8)
	s_waitcnt lgkmcnt(0)
	s_barrier
	s_setprio 1
	s_waitcnt lgkmcnt(0)
	v_mfma_f32_16x16x32_bf16 v[124:127], v[128:131], v[178:181], v[124:127]
	v_mfma_f32_16x16x32_bf16 v[120:123], v[148:151], v[178:181], v[120:123]
	v_mfma_f32_16x16x32_bf16 v[108:111], v[128:131], v[206:209], v[108:111]
	v_mfma_f32_16x16x32_bf16 v[104:107], v[148:151], v[206:209], v[104:107]
	v_mfma_f32_16x16x32_bf16 v[92:95], v[128:131], v[214:217], v[92:95]
	v_mfma_f32_16x16x32_bf16 v[88:91], v[148:151], v[214:217], v[88:91]
	v_mfma_f32_16x16x32_bf16 v[76:79], v[128:131], v[222:225], v[76:79]
	v_mfma_f32_16x16x32_bf16 v[72:75], v[148:151], v[222:225], v[72:75]
	v_mfma_f32_16x16x32_bf16 v[124:127], v[132:135], v[202:205], v[124:127]
	v_mfma_f32_16x16x32_bf16 v[120:123], v[152:155], v[202:205], v[120:123]
	v_mfma_f32_16x16x32_bf16 v[108:111], v[132:135], v[210:213], v[108:111]
	v_mfma_f32_16x16x32_bf16 v[104:107], v[152:155], v[210:213], v[104:107]
	v_mfma_f32_16x16x32_bf16 v[92:95], v[132:135], v[218:221], v[92:95]
	v_mfma_f32_16x16x32_bf16 v[88:91], v[152:155], v[218:221], v[88:91]
	v_mfma_f32_16x16x32_bf16 v[76:79], v[132:135], v[244:247], v[76:79]
	v_mfma_f32_16x16x32_bf16 v[72:75], v[152:155], v[244:247], v[72:75]
	v_mfma_f32_16x16x32_bf16 v[116:119], v[156:159], v[178:181], v[116:119]
	v_mfma_f32_16x16x32_bf16 v[112:115], v[170:173], v[178:181], v[112:115]
	v_mfma_f32_16x16x32_bf16 v[100:103], v[156:159], v[206:209], v[100:103]
	v_mfma_f32_16x16x32_bf16 v[96:99], v[170:173], v[206:209], v[96:99]
	v_mfma_f32_16x16x32_bf16 v[84:87], v[156:159], v[214:217], v[84:87]
	v_mfma_f32_16x16x32_bf16 v[80:83], v[170:173], v[214:217], v[80:83]
	v_mfma_f32_16x16x32_bf16 v[68:71], v[156:159], v[222:225], v[68:71]
	v_mfma_f32_16x16x32_bf16 v[64:67], v[170:173], v[222:225], v[64:67]
	v_mfma_f32_16x16x32_bf16 v[116:119], v[160:163], v[202:205], v[116:119]
	v_mfma_f32_16x16x32_bf16 v[112:115], v[174:177], v[202:205], v[112:115]
	v_mfma_f32_16x16x32_bf16 v[100:103], v[160:163], v[210:213], v[100:103]
	v_mfma_f32_16x16x32_bf16 v[96:99], v[174:177], v[210:213], v[96:99]
	v_mfma_f32_16x16x32_bf16 v[84:87], v[160:163], v[218:221], v[84:87]
	v_mfma_f32_16x16x32_bf16 v[80:83], v[174:177], v[218:221], v[80:83]
	v_mfma_f32_16x16x32_bf16 v[68:71], v[160:163], v[244:247], v[68:71]
	v_mfma_f32_16x16x32_bf16 v[64:67], v[174:177], v[244:247], v[64:67]
	s_setprio 0
	s_barrier
; #define PG8_STAGE(bufoff, gbase, voff) do { _Pragma("unroll") for (int _i = 0; _i < 2; ++_i) \
;         __builtin_amdgcn_global_load_lds((const unsigned*)((const char*)(gbase) + (voff)[_i]), (LAS unsigned*)(lds + (bufoff) + ldsw + _i * 8192), 16, 0, 0); } while (0)
; #define PG8_LDA(dst, b, h) do { _Pragma("unroll") for (int m = 0; m < 4; ++m) _Pragma("unroll") for (int k = 0; k < 2; ++k) dst[m][k] = *(const LAS bf16x8*)(lds + PG8_SA(b, h) + aoff + m * 2048 + k * 1024); } while (0)
; #define PG8_LDB(dst, b, h) do { _Pragma("unroll") for (int n = 0; n < 2; ++n) _Pragma("unroll") for (int k = 0; k < 2; ++k) dst[n][k] = *(const LAS bf16x8*)(lds + PG8_SB(b, h) + boff + n * 2048 + k * 1024); } while (0)
; #define PG8_MMA(ai, bj, At, Bt) do { __builtin_amdgcn_s_setprio(1); _Pragma("unroll") for (int m = 0; m < 4; ++m) _Pragma("unroll") for (int n = 0; n < 2; ++n) _Pragma("unroll") for (int k = 0; k < 2; ++k) \
;         acc[ai][bj][m][n] = __builtin_amdgcn_mfma_f32_16x16x32_bf16(Bt[n][k], At[m][k], acc[ai][bj][m][n], 0, 0, 0); __builtin_amdgcn_s_setprio(0); } while (0)
; #define PG8_WAIT_V(n) asm volatile("s_waitcnt vmcnt(" #n ")" ::: "memory")
; #define PG8_WAIT_L(n) asm volatile("s_waitcnt lgkmcnt(" #n ")" ::: "memory")
; #define PG8_BAR __builtin_amdgcn_s_barrier()
; #define PG8_SCHED __builtin_amdgcn_sched_barrier(0)
; template <class Epi>
; __device__ __forceinline__ void gemm_phase(LAS unsigned char* lds, const Gemm g, const Epi& E) {
;     ...
;             PG8_WAIT_V(8); PG8_WAIT_L(0); PG8_BAR; PG8_MMA(0, 0, At, B0); PG8_MMA(0, 1, At, B1); PG8_BAR; PG8_SCHED;
;             PG8_LDA(At, 0, 1); PG8_STAGE(PG8_SB(0, 0), b2, voffB); PG8_STAGE(PG8_SB(0, 1), b2 + hstepB, voffB); PG8_STAGE(PG8_SA(0, 0), a2, voffA);
;             PG8_WAIT_V(8); PG8_WAIT_L(0); PG8_BAR; PG8_MMA(1, 0, At, B0); PG8_MMA(1, 1, At, B1); PG8_BAR; PG8_SCHED;
;             PG8_LDB(B0, 1, 0); PG8_LDB(B1, 1, 1); PG8_SCHED; PG8_LDA(At, 1, 0); PG8_STAGE(PG8_SA(0, 1), a2 + hstepA, voffA);
;             PG8_WAIT_V(8); PG8_WAIT_L(0); PG8_BAR; PG8_MMA(0, 0, At, B0); PG8_MMA(0, 1, At, B1); PG8_BAR; PG8_SCHED;
	s_add_i32 s24, s47, 0x10000
	s_mov_b32 m0, s24
	ds_read_b128 v[178:181], v169 offset:16384
	ds_read_b128 v[202:205], v169 offset:17408
	ds_read_b128 v[206:209], v169 offset:18432
	ds_read_b128 v[210:213], v169 offset:19456
	ds_read_b128 v[214:217], v169 offset:20480
	ds_read_b128 v[218:221], v169 offset:21504
	ds_read_b128 v[222:225], v169 offset:22528
	ds_read_b128 v[244:247], v169 offset:23552
	global_load_lds_dwordx4 v138, s[38:39]
	s_add_i32 m0, s24, 0x2000
	s_add_u32 s20, s38, 0xb0000
	s_addc_u32 s21, s39, 0
	s_add_i32 s24, s47, 0x14000
	global_load_lds_dwordx4 v142, s[38:39]
	s_mov_b32 m0, s24
	s_nop 0
	global_load_lds_dwordx4 v138, s[20:21]
	s_add_i32 m0, s24, 0x2000
	s_nop 0
	global_load_lds_dwordx4 v142, s[20:21]
	s_mov_b32 m0, s48
	s_nop 0
	global_load_lds_dwordx4 v136, s[44:45]
	s_mov_b32 m0, s49
	s_nop 0
	global_load_lds_dwordx4 v140, s[44:45]
	s_waitcnt vmcnt(8)
	s_waitcnt lgkmcnt(0)
	s_barrier
	s_setprio 1
	s_waitcnt lgkmcnt(0)
	v_mfma_f32_16x16x32_bf16 v[60:63], v[128:131], v[178:181], v[60:63]
	v_mfma_f32_16x16x32_bf16 v[56:59], v[148:151], v[178:181], v[56:59]
	v_mfma_f32_16x16x32_bf16 v[44:47], v[128:131], v[206:209], v[44:47]
	v_mfma_f32_16x16x32_bf16 v[40:43], v[148:151], v[206:209], v[40:43]
	v_mfma_f32_16x16x32_bf16 v[28:31], v[128:131], v[214:217], v[28:31]
	v_mfma_f32_16x16x32_bf16 v[24:27], v[148:151], v[214:217], v[24:27]
	v_mfma_f32_16x16x32_bf16 v[12:15], v[128:131], v[222:225], v[12:15]
	v_mfma_f32_16x16x32_bf16 v[8:11], v[148:151], v[222:225], v[8:11]
	v_mfma_f32_16x16x32_bf16 v[60:63], v[132:135], v[202:205], v[60:63]
	v_mfma_f32_16x16x32_bf16 v[56:59], v[152:155], v[202:205], v[56:59]
	v_mfma_f32_16x16x32_bf16 v[44:47], v[132:135], v[210:213], v[44:47]
	v_mfma_f32_16x16x32_bf16 v[40:43], v[152:155], v[210:213], v[40:43]
	v_mfma_f32_16x16x32_bf16 v[28:31], v[132:135], v[218:221], v[28:31]
	v_mfma_f32_16x16x32_bf16 v[24:27], v[152:155], v[218:221], v[24:27]
	v_mfma_f32_16x16x32_bf16 v[12:15], v[132:135], v[244:247], v[12:15]
	v_mfma_f32_16x16x32_bf16 v[8:11], v[152:155], v[244:247], v[8:11]
	v_mfma_f32_16x16x32_bf16 v[52:55], v[156:159], v[178:181], v[52:55]
	v_mfma_f32_16x16x32_bf16 v[48:51], v[170:173], v[178:181], v[48:51]
	v_mfma_f32_16x16x32_bf16 v[36:39], v[156:159], v[206:209], v[36:39]
	v_mfma_f32_16x16x32_bf16 v[32:35], v[170:173], v[206:209], v[32:35]
	v_mfma_f32_16x16x32_bf16 v[20:23], v[156:159], v[214:217], v[20:23]
	v_mfma_f32_16x16x32_bf16 v[16:19], v[170:173], v[214:217], v[16:19]
	v_mfma_f32_16x16x32_bf16 v[4:7], v[156:159], v[222:225], v[4:7]
	v_mfma_f32_16x16x32_bf16 v[0:3], v[170:173], v[222:225], v[0:3]
	v_mfma_f32_16x16x32_bf16 v[52:55], v[160:163], v[202:205], v[52:55]
	v_mfma_f32_16x16x32_bf16 v[48:51], v[174:177], v[202:205], v[48:51]
	v_mfma_f32_16x16x32_bf16 v[36:39], v[160:163], v[210:213], v[36:39]
	v_mfma_f32_16x16x32_bf16 v[32:35], v[174:177], v[210:213], v[32:35]
	v_mfma_f32_16x16x32_bf16 v[20:23], v[160:163], v[218:221], v[20:23]
	v_mfma_f32_16x16x32_bf16 v[16:19], v[174:177], v[218:221], v[16:19]
	v_mfma_f32_16x16x32_bf16 v[4:7], v[160:163], v[244:247], v[4:7]
	v_mfma_f32_16x16x32_bf16 v[0:3], v[174:177], v[244:247], v[0:3]
	s_setprio 0
	s_barrier
	ds_read_b128 v[128:131], v182 offset:32768
	ds_read_b128 v[132:135], v182 offset:33792
	ds_read_b128 v[148:151], v182 offset:34816
	ds_read_b128 v[152:155], v182 offset:35840
	ds_read_b128 v[156:159], v182 offset:49152
	ds_read_b128 v[160:163], v182 offset:50176
	ds_read_b128 v[170:173], v182 offset:51200
	ds_read_b128 v[174:177], v182 offset:52224
	s_add_u32 s20, s44, 0xb0000
	s_addc_u32 s21, s45, 0
	s_mov_b32 m0, s54
	ds_read_b128 v[178:181], v169 offset:32768
	ds_read_b128 v[202:205], v169 offset:33792
	ds_read_b128 v[206:209], v169 offset:34816
	ds_read_b128 v[210:213], v169 offset:35840
	ds_read_b128 v[214:217], v169 offset:36864
	ds_read_b128 v[218:221], v169 offset:37888
	ds_read_b128 v[222:225], v169 offset:38912
	ds_read_b128 v[244:247], v169 offset:39936
	global_load_lds_dwordx4 v136, s[20:21]
	s_mov_b32 m0, s55
	s_nop 0
	global_load_lds_dwordx4 v140, s[20:21]
	s_waitcnt vmcnt(8)
	s_waitcnt lgkmcnt(0)
	s_barrier
; #define PG8_STAGE(bufoff, gbase, voff) do { _Pragma("unroll") for (int _i = 0; _i < 2; ++_i) \
;         __builtin_amdgcn_global_load_lds((const unsigned*)((const char*)(gbase) + (voff)[_i]), (LAS unsigned*)(lds + (bufoff) + ldsw + _i * 8192), 16, 0, 0); } while (0)
; #define PG8_LDA(dst, b, h) do { _Pragma("unroll") for (int m = 0; m < 4; ++m) _Pragma("unroll") for (int k = 0; k < 2; ++k) dst[m][k] = *(const LAS bf16x8*)(lds + PG8_SA(b, h) + aoff + m * 2048 + k * 1024); } while (0)
; #define PG8_MMA(ai, bj, At, Bt) do { __builtin_amdgcn_s_setprio(1); _Pragma("unroll") for (int m = 0; m < 4; ++m) _Pragma("unroll") for (int n = 0; n < 2; ++n) _Pragma("unroll") for (int k = 0; k < 2; ++k) \
;         acc[ai][bj][m][n] = __builtin_amdgcn_mfma_f32_16x16x32_bf16(Bt[n][k], At[m][k], acc[ai][bj][m][n], 0, 0, 0); __builtin_amdgcn_s_setprio(0); } while (0)
; #define PG8_WAIT_V(n) asm volatile("s_waitcnt vmcnt(" #n ")" ::: "memory")
; #define PG8_WAIT_L(n) asm volatile("s_waitcnt lgkmcnt(" #n ")" ::: "memory")
; #define PG8_BAR __builtin_amdgcn_s_barrier()
; #define PG8_SCHED __builtin_amdgcn_sched_barrier(0)
; template <class Epi>
; __device__ __forceinline__ void gemm_phase(LAS unsigned char* lds, const Gemm g, const Epi& E) {
;     ...
;             PG8_WAIT_V(8); PG8_WAIT_L(0); PG8_BAR; PG8_MMA(0, 0, At, B0); PG8_MMA(0, 1, At, B1); PG8_BAR; PG8_SCHED;
;             PG8_LDA(At, 1, 1); PG8_STAGE(PG8_SB(1, 0), b3, voffB); PG8_STAGE(PG8_SB(1, 1), b3 + hstepB, voffB); PG8_STAGE(PG8_SA(1, 0), a3, voffA);
;             PG8_WAIT_V(8); PG8_WAIT_L(0); PG8_BAR; PG8_MMA(1, 0, At, B0); PG8_MMA(1, 1, At, B1); PG8_BAR; PG8_SCHED;
;         }
	s_setprio 1
	s_waitcnt lgkmcnt(0)
	v_mfma_f32_16x16x32_bf16 v[124:127], v[128:131], v[178:181], v[124:127]
	v_mfma_f32_16x16x32_bf16 v[120:123], v[148:151], v[178:181], v[120:123]
	v_mfma_f32_16x16x32_bf16 v[108:111], v[128:131], v[206:209], v[108:111]
	v_mfma_f32_16x16x32_bf16 v[104:107], v[148:151], v[206:209], v[104:107]
	v_mfma_f32_16x16x32_bf16 v[92:95], v[128:131], v[214:217], v[92:95]
	v_mfma_f32_16x16x32_bf16 v[88:91], v[148:151], v[214:217], v[88:91]
	v_mfma_f32_16x16x32_bf16 v[76:79], v[128:131], v[222:225], v[76:79]
	v_mfma_f32_16x16x32_bf16 v[72:75], v[148:151], v[222:225], v[72:75]
	v_mfma_f32_16x16x32_bf16 v[124:127], v[132:135], v[202:205], v[124:127]
	v_mfma_f32_16x16x32_bf16 v[120:123], v[152:155], v[202:205], v[120:123]
	v_mfma_f32_16x16x32_bf16 v[108:111], v[132:135], v[210:213], v[108:111]
	v_mfma_f32_16x16x32_bf16 v[104:107], v[152:155], v[210:213], v[104:107]
	v_mfma_f32_16x16x32_bf16 v[92:95], v[132:135], v[218:221], v[92:95]
	v_mfma_f32_16x16x32_bf16 v[88:91], v[152:155], v[218:221], v[88:91]
	v_mfma_f32_16x16x32_bf16 v[76:79], v[132:135], v[244:247], v[76:79]
	v_mfma_f32_16x16x32_bf16 v[72:75], v[152:155], v[244:247], v[72:75]
	v_mfma_f32_16x16x32_bf16 v[116:119], v[156:159], v[178:181], v[116:119]
	v_mfma_f32_16x16x32_bf16 v[112:115], v[170:173], v[178:181], v[112:115]
	v_mfma_f32_16x16x32_bf16 v[100:103], v[156:159], v[206:209], v[100:103]
	v_mfma_f32_16x16x32_bf16 v[96:99], v[170:173], v[206:209], v[96:99]
	v_mfma_f32_16x16x32_bf16 v[84:87], v[156:159], v[214:217], v[84:87]
	v_mfma_f32_16x16x32_bf16 v[80:83], v[170:173], v[214:217], v[80:83]
	v_mfma_f32_16x16x32_bf16 v[68:71], v[156:159], v[222:225], v[68:71]
	v_mfma_f32_16x16x32_bf16 v[64:67], v[170:173], v[222:225], v[64:67]
	v_mfma_f32_16x16x32_bf16 v[116:119], v[160:163], v[202:205], v[116:119]
	v_mfma_f32_16x16x32_bf16 v[112:115], v[174:177], v[202:205], v[112:115]
	v_mfma_f32_16x16x32_bf16 v[100:103], v[160:163], v[210:213], v[100:103]
	v_mfma_f32_16x16x32_bf16 v[96:99], v[174:177], v[210:213], v[96:99]
	v_mfma_f32_16x16x32_bf16 v[84:87], v[160:163], v[218:221], v[84:87]
	v_mfma_f32_16x16x32_bf16 v[80:83], v[174:177], v[218:221], v[80:83]
	v_mfma_f32_16x16x32_bf16 v[68:71], v[160:163], v[244:247], v[68:71]
	v_mfma_f32_16x16x32_bf16 v[64:67], v[174:177], v[244:247], v[64:67]
	s_setprio 0
	s_barrier
	s_add_i32 s24, s47, 0x18000
	s_add_u32 s20, s38, 0x80
	s_addc_u32 s21, s39, 0
	s_mov_b32 m0, s24
	ds_read_b128 v[178:181], v169 offset:49152
	ds_read_b128 v[202:205], v169 offset:50176
	ds_read_b128 v[206:209], v169 offset:51200
	ds_read_b128 v[210:213], v169 offset:52224
	ds_read_b128 v[214:217], v169 offset:53248
	ds_read_b128 v[218:221], v169 offset:54272
	ds_read_b128 v[222:225], v169 offset:55296
	ds_read_b128 v[244:247], v169 offset:56320
	global_load_lds_dwordx4 v138, s[20:21]
	s_add_i32 m0, s24, 0x2000
	s_add_i32 s24, s47, 0x1c000
	global_load_lds_dwordx4 v142, s[20:21]
	s_add_u32 s20, s38, 0xb0080
	s_addc_u32 s21, s39, 0
	s_mov_b32 m0, s24
	s_nop 0
	global_load_lds_dwordx4 v138, s[20:21]
	s_add_i32 m0, s24, 0x2000
	s_nop 0
	global_load_lds_dwordx4 v142, s[20:21]
	s_add_u32 s20, s44, 0x80
	s_addc_u32 s21, s45, 0
	s_mov_b32 m0, s12
	s_nop 0
	global_load_lds_dwordx4 v136, s[20:21]
	s_mov_b32 m0, s13
	s_nop 0
	global_load_lds_dwordx4 v140, s[20:21]
	s_waitcnt vmcnt(8)
	s_waitcnt lgkmcnt(0)
	s_barrier
	s_setprio 1
	s_waitcnt lgkmcnt(0)
	v_mfma_f32_16x16x32_bf16 v[60:63], v[128:131], v[178:181], v[60:63]
	v_mfma_f32_16x16x32_bf16 v[56:59], v[148:151], v[178:181], v[56:59]
	v_mfma_f32_16x16x32_bf16 v[44:47], v[128:131], v[206:209], v[44:47]
	v_mfma_f32_16x16x32_bf16 v[40:43], v[148:151], v[206:209], v[40:43]
	v_mfma_f32_16x16x32_bf16 v[28:31], v[128:131], v[214:217], v[28:31]
	v_mfma_f32_16x16x32_bf16 v[24:27], v[148:151], v[214:217], v[24:27]
	v_mfma_f32_16x16x32_bf16 v[12:15], v[128:131], v[222:225], v[12:15]
	v_mfma_f32_16x16x32_bf16 v[8:11], v[148:151], v[222:225], v[8:11]
	v_mfma_f32_16x16x32_bf16 v[60:63], v[132:135], v[202:205], v[60:63]
	v_mfma_f32_16x16x32_bf16 v[56:59], v[152:155], v[202:205], v[56:59]
	v_mfma_f32_16x16x32_bf16 v[44:47], v[132:135], v[210:213], v[44:47]
	v_mfma_f32_16x16x32_bf16 v[40:43], v[152:155], v[210:213], v[40:43]
	v_mfma_f32_16x16x32_bf16 v[28:31], v[132:135], v[218:221], v[28:31]
	v_mfma_f32_16x16x32_bf16 v[24:27], v[152:155], v[218:221], v[24:27]
	v_mfma_f32_16x16x32_bf16 v[12:15], v[132:135], v[244:247], v[12:15]
	v_mfma_f32_16x16x32_bf16 v[8:11], v[152:155], v[244:247], v[8:11]
	v_mfma_f32_16x16x32_bf16 v[52:55], v[156:159], v[178:181], v[52:55]
	v_mfma_f32_16x16x32_bf16 v[48:51], v[170:173], v[178:181], v[48:51]
	v_mfma_f32_16x16x32_bf16 v[36:39], v[156:159], v[206:209], v[36:39]
	v_mfma_f32_16x16x32_bf16 v[32:35], v[170:173], v[206:209], v[32:35]
	v_mfma_f32_16x16x32_bf16 v[20:23], v[156:159], v[214:217], v[20:23]
	v_mfma_f32_16x16x32_bf16 v[16:19], v[170:173], v[214:217], v[16:19]
	v_mfma_f32_16x16x32_bf16 v[4:7], v[156:159], v[222:225], v[4:7]
	v_mfma_f32_16x16x32_bf16 v[0:3], v[170:173], v[222:225], v[0:3]
	v_mfma_f32_16x16x32_bf16 v[52:55], v[160:163], v[202:205], v[52:55]
	v_mfma_f32_16x16x32_bf16 v[48:51], v[174:177], v[202:205], v[48:51]
	v_mfma_f32_16x16x32_bf16 v[36:39], v[160:163], v[210:213], v[36:39]
	v_mfma_f32_16x16x32_bf16 v[32:35], v[174:177], v[210:213], v[32:35]
	v_mfma_f32_16x16x32_bf16 v[20:23], v[160:163], v[218:221], v[20:23]
	v_mfma_f32_16x16x32_bf16 v[16:19], v[174:177], v[218:221], v[16:19]
	v_mfma_f32_16x16x32_bf16 v[4:7], v[160:163], v[244:247], v[4:7]
	v_mfma_f32_16x16x32_bf16 v[0:3], v[174:177], v[244:247], v[0:3]
	s_setprio 0
	s_barrier
	s_add_i32 s82, s82, 2
	s_add_u32 s76, s76, 0x100
	s_addc_u32 s77, s77, 0
	s_cmp_gt_u32 s82, 41
	s_mov_b64 s[20:21], s[22:23]
	s_cbranch_scc0 .LBB0_501
	s_and_b64 vcc, exec, s[30:31]
	s_cbranch_vccz .LBB0_504
	s_barrier

; #define PG8_STAGE(bufoff, gbase, voff) do { _Pragma("unroll") for (int _i = 0; _i < 2; ++_i) \
;         __builtin_amdgcn_global_load_lds((const unsigned*)((const char*)(gbase) + (voff)[_i]), (LAS unsigned*)(lds + (bufoff) + ldsw + _i * 8192), 16, 0, 0); } while (0)
; #define PG8_LDA(dst, b, h) do { _Pragma("unroll") for (int m = 0; m < 4; ++m) _Pragma("unroll") for (int k = 0; k < 2; ++k) dst[m][k] = *(const LAS bf16x8*)(lds + PG8_SA(b, h) + aoff + m * 2048 + k * 1024); } while (0)
; #define PG8_LDB(dst, b, h) do { _Pragma("unroll") for (int n = 0; n < 2; ++n) _Pragma("unroll") for (int k = 0; k < 2; ++k) dst[n][k] = *(const LAS bf16x8*)(lds + PG8_SB(b, h) + boff + n * 2048 + k * 1024); } while (0)
; #define PG8_MMA(ai, bj, At, Bt) do { __builtin_amdgcn_s_setprio(1); _Pragma("unroll") for (int m = 0; m < 4; ++m) _Pragma("unroll") for (int n = 0; n < 2; ++n) _Pragma("unroll") for (int k = 0; k < 2; ++k) \
;         acc[ai][bj][m][n] = __builtin_amdgcn_mfma_f32_16x16x32_bf16(Bt[n][k], At[m][k], acc[ai][bj][m][n], 0, 0, 0); __builtin_amdgcn_s_setprio(0); } while (0)
; #define PG8_BAR __builtin_amdgcn_s_barrier()
; template <class Epi>
; __device__ __forceinline__ void gemm_phase(LAS unsigned char* lds, const Gemm g, const Epi& E) {
;     ...
;         const char* nA = has_next ? (const char*)g.A + (size_t)nxt.bz * g.strideA * 2 + (size_t)nxt.pm * tstepA : cA;
;         const char* nB = has_next ? (const char*)g.Bt + (size_t)nxt.bz * g.strideB * 2 + (size_t)nxt.pn * tstepB : cB;
;         for (int t = 0; t < nt; t += 2) {
;             const bool last = (t == nt - 2);
;             const char* a1 = cA + (size_t)(t + 1) * kstep;
;             const char* a2 = last ? nA : cA + (size_t)(t + 2) * kstep; const char* b2 = last ? nB : cB + (size_t)(t + 2) * kstep;
;             const char* a3 = a2 + kstep; const char* b3 = b2 + kstep;
;             PG8_LDB(B0, 0, 0); PG8_LDB(B1, 0, 1); PG8_SCHED; PG8_LDA(At, 0, 0); PG8_STAGE(PG8_SA(1, 1), a1 + hstepA, voffA);
;             PG8_WAIT_V(8); PG8_WAIT_L(0); PG8_BAR; PG8_MMA(0, 0, At, B0); PG8_MMA(0, 1, At, B1); PG8_BAR; PG8_SCHED;
;     ...
; #pragma unroll
;         for (int a = 0; a < 2; ++a)
; #pragma unroll
;             for (int b = 0; b < 2; ++b)
; #pragma unroll
;                 for (int m = 0; m < 4; ++m)
; #pragma unroll
;                     for (int n = 0; n < 2; ++n) acc[a][b][m][n] = (f32x4){0.f, 0.f, 0.f, 0.f};
.LBB0_991:
	s_ashr_i32 s47, s46, 31
	s_lshl_b64 s[24:25], s[46:47], 19
	s_add_u32 s56, s30, s24
	s_addc_u32 s57, s31, s25
	s_and_b64 s[24:25], s[40:41], exec
	s_cselect_b32 s43, s57, s21
	s_cselect_b32 s45, s56, s20
	s_ashr_i32 s49, s48, 31
	s_lshl_b64 s[24:25], s[48:49], 19
	s_add_u32 s68, s90, s24
	s_addc_u32 s69, s91, s25
	s_and_b64 s[24:25], s[40:41], exec
	s_cselect_b32 s47, s69, s23
	s_cselect_b32 s49, s68, s22
	s_add_u32 s20, s20, 0x40080
	s_addc_u32 s21, s21, 0
	s_add_u32 s82, s22, 0x100
	v_mov_b32_e32 v0, 0
	s_addc_u32 s83, s23, 0
	s_mov_b32 s84, -2
	v_mov_b32_e32 v1, v0
	v_mov_b32_e32 v2, v0
	v_mov_b32_e32 v3, v0
	v_mov_b32_e32 v4, v0
	v_mov_b32_e32 v5, v0
	v_mov_b32_e32 v6, v0
	v_mov_b32_e32 v7, v0
	v_mov_b32_e32 v16, v0
	v_mov_b32_e32 v17, v0
	v_mov_b32_e32 v18, v0
	v_mov_b32_e32 v19, v0
	v_mov_b32_e32 v20, v0
	v_mov_b32_e32 v21, v0
	v_mov_b32_e32 v22, v0
	v_mov_b32_e32 v23, v0
	v_mov_b32_e32 v32, v0
	v_mov_b32_e32 v33, v0
	v_mov_b32_e32 v34, v0
	v_mov_b32_e32 v35, v0
	v_mov_b32_e32 v36, v0
	v_mov_b32_e32 v37, v0
	v_mov_b32_e32 v38, v0
	v_mov_b32_e32 v39, v0
	v_mov_b32_e32 v48, v0
	v_mov_b32_e32 v49, v0
	v_mov_b32_e32 v50, v0
	v_mov_b32_e32 v51, v0
	v_mov_b32_e32 v52, v0
	v_mov_b32_e32 v53, v0
	v_mov_b32_e32 v54, v0
	v_mov_b32_e32 v55, v0
	v_mov_b32_e32 v8, v0
	v_mov_b32_e32 v9, v0
	v_mov_b32_e32 v10, v0
	v_mov_b32_e32 v11, v0
	v_mov_b32_e32 v12, v0
	v_mov_b32_e32 v13, v0
	v_mov_b32_e32 v14, v0
	v_mov_b32_e32 v15, v0
	v_mov_b32_e32 v24, v0
	v_mov_b32_e32 v25, v0
	v_mov_b32_e32 v26, v0
	v_mov_b32_e32 v27, v0
	v_mov_b32_e32 v28, v0
	v_mov_b32_e32 v29, v0
	v_mov_b32_e32 v30, v0
	v_mov_b32_e32 v31, v0
	v_mov_b32_e32 v40, v0
	v_mov_b32_e32 v41, v0
	v_mov_b32_e32 v42, v0
	v_mov_b32_e32 v43, v0
	v_mov_b32_e32 v44, v0
	v_mov_b32_e32 v45, v0
	v_mov_b32_e32 v46, v0
	v_mov_b32_e32 v47, v0
	v_mov_b32_e32 v56, v0
	v_mov_b32_e32 v57, v0
	v_mov_b32_e32 v58, v0
	v_mov_b32_e32 v59, v0
	v_mov_b32_e32 v60, v0
	v_mov_b32_e32 v61, v0
	v_mov_b32_e32 v62, v0
	v_mov_b32_e32 v63, v0
	v_mov_b32_e32 v64, v0
	v_mov_b32_e32 v65, v0
	v_mov_b32_e32 v66, v0
	v_mov_b32_e32 v67, v0
	v_mov_b32_e32 v68, v0
	v_mov_b32_e32 v69, v0
	v_mov_b32_e32 v70, v0
	v_mov_b32_e32 v71, v0
	v_mov_b32_e32 v80, v0
	v_mov_b32_e32 v81, v0
	v_mov_b32_e32 v82, v0
	v_mov_b32_e32 v83, v0
	v_mov_b32_e32 v84, v0
	v_mov_b32_e32 v85, v0
	v_mov_b32_e32 v86, v0
	v_mov_b32_e32 v87, v0
	v_mov_b32_e32 v96, v0
	v_mov_b32_e32 v97, v0
	v_mov_b32_e32 v98, v0
	v_mov_b32_e32 v99, v0
	v_mov_b32_e32 v100, v0
	v_mov_b32_e32 v101, v0
	v_mov_b32_e32 v102, v0
	v_mov_b32_e32 v103, v0
	v_mov_b32_e32 v112, v0
	v_mov_b32_e32 v113, v0
	v_mov_b32_e32 v114, v0
	v_mov_b32_e32 v115, v0
	v_mov_b32_e32 v116, v0
	v_mov_b32_e32 v117, v0
	v_mov_b32_e32 v118, v0
	v_mov_b32_e32 v119, v0
	v_mov_b32_e32 v72, v0
	v_mov_b32_e32 v73, v0
	v_mov_b32_e32 v74, v0
	v_mov_b32_e32 v75, v0
	v_mov_b32_e32 v76, v0
	v_mov_b32_e32 v77, v0
	v_mov_b32_e32 v78, v0
	v_mov_b32_e32 v79, v0
	v_mov_b32_e32 v88, v0
	v_mov_b32_e32 v89, v0
	v_mov_b32_e32 v90, v0
	v_mov_b32_e32 v91, v0
	v_mov_b32_e32 v92, v0
	v_mov_b32_e32 v93, v0
	v_mov_b32_e32 v94, v0
	v_mov_b32_e32 v95, v0
	v_mov_b32_e32 v104, v0
	v_mov_b32_e32 v105, v0
	v_mov_b32_e32 v106, v0
	v_mov_b32_e32 v107, v0
	v_mov_b32_e32 v108, v0
	v_mov_b32_e32 v109, v0
	v_mov_b32_e32 v110, v0
	v_mov_b32_e32 v111, v0
	v_mov_b32_e32 v120, v0
	v_mov_b32_e32 v121, v0
	v_mov_b32_e32 v122, v0
	v_mov_b32_e32 v123, v0
	v_mov_b32_e32 v124, v0
	v_mov_b32_e32 v125, v0
	v_mov_b32_e32 v126, v0
	v_mov_b32_e32 v127, v0
	v_add_u32_e32 v186, 0x10000, v160
.LBB0_992:
	s_add_u32 s22, s20, 0xfffc0080
	s_addc_u32 s23, s21, -1
	s_cmp_eq_u32 s84, 12
	s_cselect_b32 s55, s43, s23
	s_cselect_b32 s54, s45, s22
	s_cselect_b32 s23, s47, s83
	s_cselect_b32 s22, s49, s82
	ds_read_b128 v[144:147], v186
	ds_read_b128 v[152:155], v186 offset:1024
	ds_read_b128 v[156:159], v186 offset:2048
	ds_read_b128 v[164:167], v186 offset:3072
	ds_read_b128 v[168:171], v186 offset:16384
	ds_read_b128 v[172:175], v186 offset:17408
	ds_read_b128 v[176:179], v186 offset:18432
	ds_read_b128 v[180:183], v186 offset:19456
	s_add_i32 m0, s18, 0xc000
	ds_read_b128 v[202:205], v163
	ds_read_b128 v[206:209], v163 offset:1024
	ds_read_b128 v[210:213], v163 offset:2048
	ds_read_b128 v[214:217], v163 offset:3072
	ds_read_b128 v[218:221], v163 offset:4096
	ds_read_b128 v[222:225], v163 offset:5120
	ds_read_b128 v[244:247], v163 offset:6144
	ds_read_b128 v[248:251], v163 offset:7168
	global_load_lds_dwordx4 v140, s[20:21]
	s_add_i32 m0, s18, 0xe000
	s_nop 0
	global_load_lds_dwordx4 v142, s[20:21]
	s_waitcnt vmcnt(8)
	s_waitcnt lgkmcnt(0)
	s_barrier
; #define PG8_STAGE(bufoff, gbase, voff) do { _Pragma("unroll") for (int _i = 0; _i < 2; ++_i) \
;         __builtin_amdgcn_global_load_lds((const unsigned*)((const char*)(gbase) + (voff)[_i]), (LAS unsigned*)(lds + (bufoff) + ldsw + _i * 8192), 16, 0, 0); } while (0)
; #define PG8_LDA(dst, b, h) do { _Pragma("unroll") for (int m = 0; m < 4; ++m) _Pragma("unroll") for (int k = 0; k < 2; ++k) dst[m][k] = *(const LAS bf16x8*)(lds + PG8_SA(b, h) + aoff + m * 2048 + k * 1024); } while (0)
; #define PG8_MMA(ai, bj, At, Bt) do { __builtin_amdgcn_s_setprio(1); _Pragma("unroll") for (int m = 0; m < 4; ++m) _Pragma("unroll") for (int n = 0; n < 2; ++n) _Pragma("unroll") for (int k = 0; k < 2; ++k) \
;         acc[ai][bj][m][n] = __builtin_amdgcn_mfma_f32_16x16x32_bf16(Bt[n][k], At[m][k], acc[ai][bj][m][n], 0, 0, 0); __builtin_amdgcn_s_setprio(0); } while (0)
; #define PG8_WAIT_V(n) asm volatile("s_waitcnt vmcnt(" #n ")" ::: "memory")
; #define PG8_WAIT_L(n) asm volatile("s_waitcnt lgkmcnt(" #n ")" ::: "memory")
; #define PG8_BAR __builtin_amdgcn_s_barrier()
; #define PG8_SCHED __builtin_amdgcn_sched_barrier(0)
; template <class Epi>
; __device__ __forceinline__ void gemm_phase(LAS unsigned char* lds, const Gemm g, const Epi& E) {
;     ...
;             PG8_WAIT_V(8); PG8_WAIT_L(0); PG8_BAR; PG8_MMA(0, 0, At, B0); PG8_MMA(0, 1, At, B1); PG8_BAR; PG8_SCHED;
;             PG8_LDA(At, 0, 1); PG8_STAGE(PG8_SB(0, 0), b2, voffB); PG8_STAGE(PG8_SB(0, 1), b2 + hstepB, voffB); PG8_STAGE(PG8_SA(0, 0), a2, voffA);
;             PG8_WAIT_V(8); PG8_WAIT_L(0); PG8_BAR; PG8_MMA(1, 0, At, B0); PG8_MMA(1, 1, At, B1); PG8_BAR; PG8_SCHED;
	s_setprio 1
	s_waitcnt lgkmcnt(0)
	v_mfma_f32_16x16x32_bf16 v[124:127], v[144:147], v[202:205], v[124:127]
	v_mfma_f32_16x16x32_bf16 v[120:123], v[156:159], v[202:205], v[120:123]
	v_mfma_f32_16x16x32_bf16 v[108:111], v[144:147], v[210:213], v[108:111]
	v_mfma_f32_16x16x32_bf16 v[104:107], v[156:159], v[210:213], v[104:107]
	v_mfma_f32_16x16x32_bf16 v[92:95], v[144:147], v[218:221], v[92:95]
	v_mfma_f32_16x16x32_bf16 v[88:91], v[156:159], v[218:221], v[88:91]
	v_mfma_f32_16x16x32_bf16 v[76:79], v[144:147], v[244:247], v[76:79]
	v_mfma_f32_16x16x32_bf16 v[72:75], v[156:159], v[244:247], v[72:75]
	v_mfma_f32_16x16x32_bf16 v[124:127], v[152:155], v[206:209], v[124:127]
	v_mfma_f32_16x16x32_bf16 v[120:123], v[164:167], v[206:209], v[120:123]
	v_mfma_f32_16x16x32_bf16 v[108:111], v[152:155], v[214:217], v[108:111]
	v_mfma_f32_16x16x32_bf16 v[104:107], v[164:167], v[214:217], v[104:107]
	v_mfma_f32_16x16x32_bf16 v[92:95], v[152:155], v[222:225], v[92:95]
	v_mfma_f32_16x16x32_bf16 v[88:91], v[164:167], v[222:225], v[88:91]
	v_mfma_f32_16x16x32_bf16 v[76:79], v[152:155], v[248:251], v[76:79]
	v_mfma_f32_16x16x32_bf16 v[72:75], v[164:167], v[248:251], v[72:75]
	v_mfma_f32_16x16x32_bf16 v[116:119], v[168:171], v[202:205], v[116:119]
	v_mfma_f32_16x16x32_bf16 v[112:115], v[176:179], v[202:205], v[112:115]
	v_mfma_f32_16x16x32_bf16 v[100:103], v[168:171], v[210:213], v[100:103]
	v_mfma_f32_16x16x32_bf16 v[96:99], v[176:179], v[210:213], v[96:99]
	v_mfma_f32_16x16x32_bf16 v[84:87], v[168:171], v[218:221], v[84:87]
	v_mfma_f32_16x16x32_bf16 v[80:83], v[176:179], v[218:221], v[80:83]
	v_mfma_f32_16x16x32_bf16 v[68:71], v[168:171], v[244:247], v[68:71]
	v_mfma_f32_16x16x32_bf16 v[64:67], v[176:179], v[244:247], v[64:67]
	v_mfma_f32_16x16x32_bf16 v[116:119], v[172:175], v[206:209], v[116:119]
	v_mfma_f32_16x16x32_bf16 v[112:115], v[180:183], v[206:209], v[112:115]
	v_mfma_f32_16x16x32_bf16 v[100:103], v[172:175], v[214:217], v[100:103]
	v_mfma_f32_16x16x32_bf16 v[96:99], v[180:183], v[214:217], v[96:99]
	v_mfma_f32_16x16x32_bf16 v[84:87], v[172:175], v[222:225], v[84:87]
	v_mfma_f32_16x16x32_bf16 v[80:83], v[180:183], v[222:225], v[80:83]
	v_mfma_f32_16x16x32_bf16 v[68:71], v[172:175], v[248:251], v[68:71]
	v_mfma_f32_16x16x32_bf16 v[64:67], v[180:183], v[248:251], v[64:67]
	s_setprio 0
	s_barrier
	s_add_i32 s85, s17, 0x10000
	s_mov_b32 m0, s85
	ds_read_b128 v[202:205], v163 offset:16384
	ds_read_b128 v[206:209], v163 offset:17408
	ds_read_b128 v[210:213], v163 offset:18432
	ds_read_b128 v[214:217], v163 offset:19456
	ds_read_b128 v[218:221], v163 offset:20480
	ds_read_b128 v[222:225], v163 offset:21504
	ds_read_b128 v[244:247], v163 offset:22528
	ds_read_b128 v[248:251], v163 offset:23552
	global_load_lds_dwordx4 v130, s[22:23]
	s_add_i32 m0, s85, 0x2000
	s_add_u32 s24, s22, 0x40000
	s_addc_u32 s25, s23, 0
	s_add_i32 s85, s17, 0x14000
	global_load_lds_dwordx4 v134, s[22:23]
	s_mov_b32 m0, s85
	s_nop 0
	global_load_lds_dwordx4 v130, s[24:25]
	s_add_i32 m0, s85, 0x2000
	s_nop 0
	global_load_lds_dwordx4 v134, s[24:25]
	s_mov_b32 m0, s18
	s_nop 0
	global_load_lds_dwordx4 v128, s[54:55]
	s_mov_b32 m0, s19
	s_nop 0
	global_load_lds_dwordx4 v132, s[54:55]
	s_waitcnt vmcnt(8)
	s_waitcnt lgkmcnt(0)
	s_barrier
	s_setprio 1
	s_waitcnt lgkmcnt(0)
	v_mfma_f32_16x16x32_bf16 v[60:63], v[144:147], v[202:205], v[60:63]
	v_mfma_f32_16x16x32_bf16 v[56:59], v[156:159], v[202:205], v[56:59]
	v_mfma_f32_16x16x32_bf16 v[44:47], v[144:147], v[210:213], v[44:47]
	v_mfma_f32_16x16x32_bf16 v[40:43], v[156:159], v[210:213], v[40:43]
	v_mfma_f32_16x16x32_bf16 v[28:31], v[144:147], v[218:221], v[28:31]
	v_mfma_f32_16x16x32_bf16 v[24:27], v[156:159], v[218:221], v[24:27]
	v_mfma_f32_16x16x32_bf16 v[12:15], v[144:147], v[244:247], v[12:15]
	v_mfma_f32_16x16x32_bf16 v[8:11], v[156:159], v[244:247], v[8:11]
	v_mfma_f32_16x16x32_bf16 v[60:63], v[152:155], v[206:209], v[60:63]
	v_mfma_f32_16x16x32_bf16 v[56:59], v[164:167], v[206:209], v[56:59]
	v_mfma_f32_16x16x32_bf16 v[44:47], v[152:155], v[214:217], v[44:47]
	v_mfma_f32_16x16x32_bf16 v[40:43], v[164:167], v[214:217], v[40:43]
	v_mfma_f32_16x16x32_bf16 v[28:31], v[152:155], v[222:225], v[28:31]
	v_mfma_f32_16x16x32_bf16 v[24:27], v[164:167], v[222:225], v[24:27]
	v_mfma_f32_16x16x32_bf16 v[12:15], v[152:155], v[248:251], v[12:15]
	v_mfma_f32_16x16x32_bf16 v[8:11], v[164:167], v[248:251], v[8:11]
	v_mfma_f32_16x16x32_bf16 v[52:55], v[168:171], v[202:205], v[52:55]
	v_mfma_f32_16x16x32_bf16 v[48:51], v[176:179], v[202:205], v[48:51]
	v_mfma_f32_16x16x32_bf16 v[36:39], v[168:171], v[210:213], v[36:39]
	v_mfma_f32_16x16x32_bf16 v[32:35], v[176:179], v[210:213], v[32:35]
	v_mfma_f32_16x16x32_bf16 v[20:23], v[168:171], v[218:221], v[20:23]
	v_mfma_f32_16x16x32_bf16 v[16:19], v[176:179], v[218:221], v[16:19]
	v_mfma_f32_16x16x32_bf16 v[4:7], v[168:171], v[244:247], v[4:7]
	v_mfma_f32_16x16x32_bf16 v[0:3], v[176:179], v[244:247], v[0:3]
	v_mfma_f32_16x16x32_bf16 v[52:55], v[172:175], v[206:209], v[52:55]
	v_mfma_f32_16x16x32_bf16 v[48:51], v[180:183], v[206:209], v[48:51]
	v_mfma_f32_16x16x32_bf16 v[36:39], v[172:175], v[214:217], v[36:39]
	v_mfma_f32_16x16x32_bf16 v[32:35], v[180:183], v[214:217], v[32:35]
	v_mfma_f32_16x16x32_bf16 v[20:23], v[172:175], v[222:225], v[20:23]
	v_mfma_f32_16x16x32_bf16 v[16:19], v[180:183], v[222:225], v[16:19]
	v_mfma_f32_16x16x32_bf16 v[4:7], v[172:175], v[248:251], v[4:7]
	v_mfma_f32_16x16x32_bf16 v[0:3], v[180:183], v[248:251], v[0:3]
	s_setprio 0
	s_barrier
; #define PG8_STAGE(bufoff, gbase, voff) do { _Pragma("unroll") for (int _i = 0; _i < 2; ++_i) \
;         __builtin_amdgcn_global_load_lds((const unsigned*)((const char*)(gbase) + (voff)[_i]), (LAS unsigned*)(lds + (bufoff) + ldsw + _i * 8192), 16, 0, 0); } while (0)
; #define PG8_LDA(dst, b, h) do { _Pragma("unroll") for (int m = 0; m < 4; ++m) _Pragma("unroll") for (int k = 0; k < 2; ++k) dst[m][k] = *(const LAS bf16x8*)(lds + PG8_SA(b, h) + aoff + m * 2048 + k * 1024); } while (0)
; #define PG8_LDB(dst, b, h) do { _Pragma("unroll") for (int n = 0; n < 2; ++n) _Pragma("unroll") for (int k = 0; k < 2; ++k) dst[n][k] = *(const LAS bf16x8*)(lds + PG8_SB(b, h) + boff + n * 2048 + k * 1024); } while (0)
; #define PG8_MMA(ai, bj, At, Bt) do { __builtin_amdgcn_s_setprio(1); _Pragma("unroll") for (int m = 0; m < 4; ++m) _Pragma("unroll") for (int n = 0; n < 2; ++n) _Pragma("unroll") for (int k = 0; k < 2; ++k) \
;         acc[ai][bj][m][n] = __builtin_amdgcn_mfma_f32_16x16x32_bf16(Bt[n][k], At[m][k], acc[ai][bj][m][n], 0, 0, 0); __builtin_amdgcn_s_setprio(0); } while (0)
; #define PG8_WAIT_V(n) asm volatile("s_waitcnt vmcnt(" #n ")" ::: "memory")
; #define PG8_WAIT_L(n) asm volatile("s_waitcnt lgkmcnt(" #n ")" ::: "memory")
; #define PG8_BAR __builtin_amdgcn_s_barrier()
; #define PG8_SCHED __builtin_amdgcn_sched_barrier(0)
; template <class Epi>
; __device__ __forceinline__ void gemm_phase(LAS unsigned char* lds, const Gemm g, const Epi& E) {
;     ...
;             PG8_LDB(B0, 1, 0); PG8_LDB(B1, 1, 1); PG8_SCHED; PG8_LDA(At, 1, 0); PG8_STAGE(PG8_SA(0, 1), a2 + hstepA, voffA);
;             PG8_WAIT_V(8); PG8_WAIT_L(0); PG8_BAR; PG8_MMA(0, 0, At, B0); PG8_MMA(0, 1, At, B1); PG8_BAR; PG8_SCHED;
;             PG8_LDA(At, 1, 1); PG8_STAGE(PG8_SB(1, 0), b3, voffB); PG8_STAGE(PG8_SB(1, 1), b3 + hstepB, voffB); PG8_STAGE(PG8_SA(1, 0), a3, voffA);
;             PG8_WAIT_V(8); PG8_WAIT_L(0); PG8_BAR; PG8_MMA(1, 0, At, B0); PG8_MMA(1, 1, At, B1); PG8_BAR; PG8_SCHED;
;         }
	ds_read_b128 v[144:147], v186 offset:32768
	ds_read_b128 v[152:155], v186 offset:33792
	ds_read_b128 v[156:159], v186 offset:34816
	ds_read_b128 v[164:167], v186 offset:35840
	ds_read_b128 v[168:171], v186 offset:49152
	ds_read_b128 v[172:175], v186 offset:50176
	ds_read_b128 v[176:179], v186 offset:51200
	ds_read_b128 v[180:183], v186 offset:52224
	s_add_u32 s24, s54, 0x40000
	s_addc_u32 s25, s55, 0
	s_mov_b32 m0, s26
	ds_read_b128 v[202:205], v163 offset:32768
	ds_read_b128 v[206:209], v163 offset:33792
	ds_read_b128 v[210:213], v163 offset:34816
	ds_read_b128 v[214:217], v163 offset:35840
	ds_read_b128 v[218:221], v163 offset:36864
	ds_read_b128 v[222:225], v163 offset:37888
	ds_read_b128 v[244:247], v163 offset:38912
	ds_read_b128 v[248:251], v163 offset:39936
	global_load_lds_dwordx4 v128, s[24:25]
	s_mov_b32 m0, s27
	s_nop 0
	global_load_lds_dwordx4 v132, s[24:25]
	s_waitcnt vmcnt(8)
	s_waitcnt lgkmcnt(0)
	s_barrier
	s_setprio 1
	s_waitcnt lgkmcnt(0)
	v_mfma_f32_16x16x32_bf16 v[124:127], v[144:147], v[202:205], v[124:127]
	v_mfma_f32_16x16x32_bf16 v[120:123], v[156:159], v[202:205], v[120:123]
	v_mfma_f32_16x16x32_bf16 v[108:111], v[144:147], v[210:213], v[108:111]
	v_mfma_f32_16x16x32_bf16 v[104:107], v[156:159], v[210:213], v[104:107]
	v_mfma_f32_16x16x32_bf16 v[92:95], v[144:147], v[218:221], v[92:95]
	v_mfma_f32_16x16x32_bf16 v[88:91], v[156:159], v[218:221], v[88:91]
	v_mfma_f32_16x16x32_bf16 v[76:79], v[144:147], v[244:247], v[76:79]
	v_mfma_f32_16x16x32_bf16 v[72:75], v[156:159], v[244:247], v[72:75]
	v_mfma_f32_16x16x32_bf16 v[124:127], v[152:155], v[206:209], v[124:127]
	v_mfma_f32_16x16x32_bf16 v[120:123], v[164:167], v[206:209], v[120:123]
	v_mfma_f32_16x16x32_bf16 v[108:111], v[152:155], v[214:217], v[108:111]
	v_mfma_f32_16x16x32_bf16 v[104:107], v[164:167], v[214:217], v[104:107]
	v_mfma_f32_16x16x32_bf16 v[92:95], v[152:155], v[222:225], v[92:95]
	v_mfma_f32_16x16x32_bf16 v[88:91], v[164:167], v[222:225], v[88:91]
	v_mfma_f32_16x16x32_bf16 v[76:79], v[152:155], v[248:251], v[76:79]
	v_mfma_f32_16x16x32_bf16 v[72:75], v[164:167], v[248:251], v[72:75]
	v_mfma_f32_16x16x32_bf16 v[116:119], v[168:171], v[202:205], v[116:119]
	v_mfma_f32_16x16x32_bf16 v[112:115], v[176:179], v[202:205], v[112:115]
	v_mfma_f32_16x16x32_bf16 v[100:103], v[168:171], v[210:213], v[100:103]
	v_mfma_f32_16x16x32_bf16 v[96:99], v[176:179], v[210:213], v[96:99]
	v_mfma_f32_16x16x32_bf16 v[84:87], v[168:171], v[218:221], v[84:87]
	v_mfma_f32_16x16x32_bf16 v[80:83], v[176:179], v[218:221], v[80:83]
	v_mfma_f32_16x16x32_bf16 v[68:71], v[168:171], v[244:247], v[68:71]
	v_mfma_f32_16x16x32_bf16 v[64:67], v[176:179], v[244:247], v[64:67]
	v_mfma_f32_16x16x32_bf16 v[116:119], v[172:175], v[206:209], v[116:119]
	v_mfma_f32_16x16x32_bf16 v[112:115], v[180:183], v[206:209], v[112:115]
	v_mfma_f32_16x16x32_bf16 v[100:103], v[172:175], v[214:217], v[100:103]
	v_mfma_f32_16x16x32_bf16 v[96:99], v[180:183], v[214:217], v[96:99]
	v_mfma_f32_16x16x32_bf16 v[84:87], v[172:175], v[222:225], v[84:87]
	v_mfma_f32_16x16x32_bf16 v[80:83], v[180:183], v[222:225], v[80:83]
	v_mfma_f32_16x16x32_bf16 v[68:71], v[172:175], v[248:251], v[68:71]
	v_mfma_f32_16x16x32_bf16 v[64:67], v[180:183], v[248:251], v[64:67]
	s_setprio 0
	s_barrier
	s_add_i32 s85, s17, 0x18000
	s_add_u32 s24, s22, 0x80
	s_addc_u32 s25, s23, 0
	s_mov_b32 m0, s85
	ds_read_b128 v[202:205], v163 offset:49152
	ds_read_b128 v[206:209], v163 offset:50176
	ds_read_b128 v[210:213], v163 offset:51200
	ds_read_b128 v[214:217], v163 offset:52224
	ds_read_b128 v[218:221], v163 offset:53248
	ds_read_b128 v[222:225], v163 offset:54272
	ds_read_b128 v[244:247], v163 offset:55296
	ds_read_b128 v[248:251], v163 offset:56320
	global_load_lds_dwordx4 v130, s[24:25]
	s_add_i32 m0, s85, 0x2000
	s_add_u32 s22, s22, 0x40080
	s_addc_u32 s23, s23, 0
	s_add_i32 s85, s17, 0x1c000
	global_load_lds_dwordx4 v134, s[24:25]
	s_mov_b32 m0, s85
	s_nop 0
	global_load_lds_dwordx4 v130, s[22:23]
	s_add_i32 m0, s85, 0x2000
	s_nop 0
	global_load_lds_dwordx4 v134, s[22:23]
	s_add_u32 s24, s54, 0x80
	s_addc_u32 s25, s55, 0
	s_mov_b32 m0, s66
	s_nop 0
	global_load_lds_dwordx4 v128, s[24:25]
	s_mov_b32 m0, s76
	s_nop 0
	global_load_lds_dwordx4 v132, s[24:25]
	s_waitcnt vmcnt(8)
	s_waitcnt lgkmcnt(0)
	s_barrier
	s_setprio 1
	s_waitcnt lgkmcnt(0)
	v_mfma_f32_16x16x32_bf16 v[60:63], v[144:147], v[202:205], v[60:63]
	v_mfma_f32_16x16x32_bf16 v[56:59], v[156:159], v[202:205], v[56:59]
	v_mfma_f32_16x16x32_bf16 v[44:47], v[144:147], v[210:213], v[44:47]
	v_mfma_f32_16x16x32_bf16 v[40:43], v[156:159], v[210:213], v[40:43]
	v_mfma_f32_16x16x32_bf16 v[28:31], v[144:147], v[218:221], v[28:31]
	v_mfma_f32_16x16x32_bf16 v[24:27], v[156:159], v[218:221], v[24:27]
	v_mfma_f32_16x16x32_bf16 v[12:15], v[144:147], v[244:247], v[12:15]
	v_mfma_f32_16x16x32_bf16 v[8:11], v[156:159], v[244:247], v[8:11]
	v_mfma_f32_16x16x32_bf16 v[60:63], v[152:155], v[206:209], v[60:63]
	v_mfma_f32_16x16x32_bf16 v[56:59], v[164:167], v[206:209], v[56:59]
	v_mfma_f32_16x16x32_bf16 v[44:47], v[152:155], v[214:217], v[44:47]
	v_mfma_f32_16x16x32_bf16 v[40:43], v[164:167], v[214:217], v[40:43]
	v_mfma_f32_16x16x32_bf16 v[28:31], v[152:155], v[222:225], v[28:31]
	v_mfma_f32_16x16x32_bf16 v[24:27], v[164:167], v[222:225], v[24:27]
	v_mfma_f32_16x16x32_bf16 v[12:15], v[152:155], v[248:251], v[12:15]
	v_mfma_f32_16x16x32_bf16 v[8:11], v[164:167], v[248:251], v[8:11]
	v_mfma_f32_16x16x32_bf16 v[52:55], v[168:171], v[202:205], v[52:55]
	v_mfma_f32_16x16x32_bf16 v[48:51], v[176:179], v[202:205], v[48:51]
	v_mfma_f32_16x16x32_bf16 v[36:39], v[168:171], v[210:213], v[36:39]
	v_mfma_f32_16x16x32_bf16 v[32:35], v[176:179], v[210:213], v[32:35]
	v_mfma_f32_16x16x32_bf16 v[20:23], v[168:171], v[218:221], v[20:23]
	v_mfma_f32_16x16x32_bf16 v[16:19], v[176:179], v[218:221], v[16:19]
	v_mfma_f32_16x16x32_bf16 v[4:7], v[168:171], v[244:247], v[4:7]
	v_mfma_f32_16x16x32_bf16 v[0:3], v[176:179], v[244:247], v[0:3]
	v_mfma_f32_16x16x32_bf16 v[52:55], v[172:175], v[206:209], v[52:55]
	v_mfma_f32_16x16x32_bf16 v[48:51], v[180:183], v[206:209], v[48:51]
	v_mfma_f32_16x16x32_bf16 v[36:39], v[172:175], v[214:217], v[36:39]
	v_mfma_f32_16x16x32_bf16 v[32:35], v[180:183], v[214:217], v[32:35]
	v_mfma_f32_16x16x32_bf16 v[20:23], v[172:175], v[222:225], v[20:23]
	v_mfma_f32_16x16x32_bf16 v[16:19], v[180:183], v[222:225], v[16:19]
	v_mfma_f32_16x16x32_bf16 v[4:7], v[172:175], v[248:251], v[4:7]
	v_mfma_f32_16x16x32_bf16 v[0:3], v[180:183], v[248:251], v[0:3]
	s_setprio 0
	s_barrier
	s_add_i32 s84, s84, 2
	s_add_u32 s20, s20, 0x100
	s_addc_u32 s21, s21, 0
	s_add_u32 s82, s82, 0x100
	s_addc_u32 s83, s83, 0
	s_cmp_gt_u32 s84, 13
	s_cbranch_scc0 .LBB0_992
	s_and_b64 vcc, exec, s[38:39]
	s_cbranch_vccz .LBB0_995
	s_barrier
